# convert_mixer(L+1) also moved (before the barrier after FFN-up) and handed out dynamically in blocks of 8 items per workgroup claim; w_s conversion stays static
# speedup vs baseline: 1.0154x; 1.0063x over previous
.LBB0_489:
	s_cmp_gt_u32 s40, 5
	s_cbranch_scc1 .Lmy_cvm_skip
	v_mov_b32_e32 v37, v237
	v_readlane_b32 s6, v254, 0
	v_readfirstlane_b32 s5, v37
	s_ashr_i32 s5, s5, 6
	s_add_i32 s12, s5, s6
	s_mov_b32 s101, s12
	v_readfirstlane_b32 s100, v237
	s_cmp_gt_u32 s100, 63
	s_cbranch_scc1 .Lmy_cv5_w
	s_mov_b64 s[44:45], exec
	s_mov_b64 exec, 1
	s_lshl_b32 s100, s40, 8
	s_add_i32 s100, s100, 0x5000
	v_mov_b32_e32 v90, s100
	v_mov_b32_e32 v91, 1
	global_atomic_add v91, v90, v91, s[36:37] sc0
	v_mov_b32_e32 v90, 0x21008
	s_waitcnt vmcnt(0)
	ds_write_b32 v90, v91
	s_waitcnt lgkmcnt(0)
	s_mov_b64 exec, s[44:45]
.Lmy_cv5_w:
	s_barrier
	v_mov_b32_e32 v90, 0x21008
	ds_read_b32 v90, v90
	s_waitcnt lgkmcnt(0)
	s_barrier
	v_readfirstlane_b32 s12, v90
	v_readfirstlane_b32 s100, v237
	s_lshr_b32 s100, s100, 6
	s_lshl_b32 s12, s12, 3
	s_add_i32 s12, s12, s100
	s_load_dwordx2 s[6:7], s[0:1], 0x80
	s_add_i32 s4, s56, 1
	s_lshl_b32 s5, s5, 14
	s_add_i32 s13, s5, 0
	s_lshr_b32 s42, s4, 1
	s_lshl_b32 s4, s4, 12
	s_waitcnt lgkmcnt(0)
	s_add_u32 s6, s6, s4
	v_and_b32_e32 v36, 63, v37
	s_addc_u32 s7, s7, 0
	s_andn2_b64 vcc, exec, s[58:59]
	s_mov_b64 s[4:5], -1
	s_cbranch_vccnz .LBB0_301
	s_load_dwordx2 s[8:9], s[0:1], 0x8
	s_mul_i32 s5, s42, 0x600000
	s_mul_hi_u32 s4, s42, 0x600000
	s_waitcnt lgkmcnt(0)
	s_add_u32 s14, s8, s5
	s_addc_u32 s15, s9, s4
	s_load_dwordx2 s[8:9], s[0:1], 0x20
	s_lshl_b64 s[4:5], s[42:43], 22
	s_waitcnt lgkmcnt(0)
	s_add_u32 s16, s8, s4
	s_addc_u32 s17, s9, s5
	s_cmpk_lt_i32 s12, 0x500
	s_cselect_b64 s[8:9], -1, 0
	s_cmpk_gt_i32 s12, 0x4ff
	s_cbranch_scc1 .LBB0_231
	s_cmpk_gt_i32 s12, 0x2ff
	s_cselect_b64 s[4:5], -1, 0
	s_and_b64 s[10:11], s[4:5], exec
	s_movk_i32 s10, 0x600
	s_cselect_b32 s18, 0x400, s10
	s_cselect_b32 s20, 0xfffffd00, 0
	s_lshr_b32 s19, s18, 5
	s_abs_i32 s10, s19
	v_cvt_f32_u32_e32 v0, s10
	s_sub_i32 s22, 0, s10
	s_add_i32 s20, s20, s12
	s_abs_i32 s21, s20
	v_rcp_iflag_f32_e32 v0, v0
	s_xor_b32 s11, s20, s19
	s_ashr_i32 s11, s11, 31
	v_lshrrev_b32_e32 v2, 5, v36
	v_mul_f32_e32 v0, 0x4f7ffffe, v0
	v_cvt_u32_f32_e32 v0, v0
	v_mov_b32_e32 v8, 1.0
	v_readfirstlane_b32 s23, v0
	s_mul_i32 s22, s22, s23
	s_mul_hi_u32 s22, s23, s22
	s_add_i32 s23, s23, s22
	s_mul_hi_u32 s22, s21, s23
	s_mul_i32 s23, s22, s10
	s_sub_i32 s21, s21, s23
	s_add_i32 s24, s22, 1
	s_sub_i32 s23, s21, s10
	s_cmp_ge_u32 s21, s10
	s_cselect_b32 s22, s24, s22
	s_cselect_b32 s21, s23, s21
	s_add_i32 s23, s22, 1
	s_cmp_ge_u32 s21, s10
	s_cselect_b32 s10, s23, s22
	s_xor_b32 s10, s10, s11
	s_sub_i32 s21, s10, s11
	v_lshl_or_b32 v2, s21, 6, v2
	s_or_b64 s[10:11], s[4:5], s[92:93]
	v_ashrrev_i32_e32 v3, 31, v2
	s_and_b64 vcc, exec, s[10:11]
	v_lshl_add_u64 v[6:7], v[2:3], 2, s[6:7]
	v_mov_b32_e32 v3, 1.0
	s_cbranch_vccnz .LBB0_168
	global_load_dword v3, v[6:7], off

.LBB0_235:
	v_add_u32_e32 v35, 0x400, v44
	ds_write2_b32 v44, v2, v3 offset1:66
	ds_write2_b32 v44, v4, v5 offset0:132 offset1:198
	ds_write2_b32 v35, v6, v7 offset0:8 offset1:74
	ds_write2_b32 v35, v8, v9 offset0:140 offset1:206
	v_add_u32_e32 v35, 0x800, v44
	ds_write2_b32 v35, v10, v11 offset0:16 offset1:82
	ds_write2_b32 v35, v12, v13 offset0:148 offset1:214
	v_add_u32_e32 v35, 0xc00, v44
	v_readfirstlane_b32 s100, v237
	s_cmp_gt_u32 s100, 63
	s_cbranch_scc1 .Lmy_cv4_w
	s_mov_b64 s[44:45], exec
	s_mov_b64 exec, 1
	s_lshl_b32 s100, s40, 8
	s_add_i32 s100, s100, 0x5000
	v_mov_b32_e32 v90, s100
	v_mov_b32_e32 v91, 1
	global_atomic_add v91, v90, v91, s[36:37] sc0
	v_mov_b32_e32 v90, 0x21008
	s_waitcnt vmcnt(0)
	ds_write_b32 v90, v91
	s_waitcnt lgkmcnt(0)
	s_mov_b64 exec, s[44:45]
.Lmy_cv4_w:
	s_barrier
	v_mov_b32_e32 v90, 0x21008
	ds_read_b32 v90, v90
	s_waitcnt lgkmcnt(0)
	s_barrier
	v_readfirstlane_b32 s18, v90
	v_readfirstlane_b32 s100, v237
	s_lshr_b32 s100, s100, 6
	s_lshl_b32 s18, s18, 3
	s_add_i32 s18, s18, s100
	ds_write2_b32 v35, v14, v15 offset0:24 offset1:90
	ds_write2_b32 v35, v16, v17 offset0:156 offset1:222
	v_add_u32_e32 v35, 0x1000, v44
	ds_write2_b32 v35, v18, v19 offset0:32 offset1:98
	ds_write2_b32 v35, v20, v21 offset0:164 offset1:230
	v_add_u32_e32 v35, 0x1400, v44
	s_cmpk_gt_i32 s18, 0x4ff
	ds_write2_b32 v35, v22, v23 offset0:40 offset1:106
	ds_write2_b32 v35, v24, v25 offset0:172 offset1:238
	v_add_u32_e32 v35, 0x1800, v44
	s_cselect_b64 s[8:9], -1, 0
	ds_write2_b32 v35, v26, v27 offset0:48 offset1:114
	ds_write2_b32 v35, v28, v29 offset0:180 offset1:246
	v_add_u32_e32 v35, 0x1c00, v44
	s_and_b64 vcc, exec, s[8:9]
	ds_write2_b32 v35, v30, v31 offset0:56 offset1:122
	ds_write2_b32 v35, v32, v33 offset0:188 offset1:254
	s_cbranch_vccnz .LBB0_234
	s_cmpk_gt_i32 s18, 0x2ff
	s_cselect_b64 s[4:5], -1, 0
	s_and_b64 s[10:11], s[4:5], exec
	s_movk_i32 s10, 0x600
	s_cselect_b32 s20, 0x400, s10
	s_cselect_b32 s10, 0xfffffd00, 0
	s_lshr_b32 s21, s20, 5
	s_abs_i32 s11, s21
	v_cvt_f32_u32_e32 v2, s11
	s_sub_i32 s24, 0, s11
	s_add_i32 s22, s18, s10
	v_rcp_iflag_f32_e32 v2, v2
	s_abs_i32 s23, s22
	s_xor_b32 s10, s22, s21
	s_ashr_i32 s10, s10, 31
	v_mul_f32_e32 v2, 0x4f7ffffe, v2
	v_cvt_u32_f32_e32 v2, v2
	v_mov_b32_e32 v8, 1.0
	v_readfirstlane_b32 s25, v2
	s_mul_i32 s24, s24, s25
	s_mul_hi_u32 s24, s25, s24
	s_add_i32 s25, s25, s24
	s_mul_hi_u32 s24, s23, s25
	s_mul_i32 s25, s24, s11
	s_sub_i32 s23, s23, s25
	s_add_i32 s26, s24, 1
	s_sub_i32 s25, s23, s11
	s_cmp_ge_u32 s23, s11
	s_cselect_b32 s24, s26, s24
	s_cselect_b32 s23, s25, s23
	s_add_i32 s25, s24, 1
	s_cmp_ge_u32 s23, s11
	s_cselect_b32 s11, s25, s24
	s_xor_b32 s11, s11, s10
	s_sub_i32 s23, s11, s10
	v_lshl_or_b32 v2, s23, 6, v38
	s_or_b64 s[10:11], s[4:5], s[92:93]
	v_ashrrev_i32_e32 v3, 31, v2
	s_and_b64 vcc, exec, s[10:11]
	v_lshl_add_u64 v[6:7], v[2:3], 2, s[6:7]
	v_mov_b32_e32 v3, 1.0
	s_cbranch_vccnz .LBB0_238
	global_load_dword v3, v[6:7], off

.LBB0_372:
	v_add_u32_e32 v35, 0x400, v43
	ds_write2_b32 v43, v2, v3 offset1:66
	ds_write2_b32 v43, v4, v5 offset0:132 offset1:198
	ds_write2_b32 v35, v6, v7 offset0:8 offset1:74
	ds_write2_b32 v35, v8, v9 offset0:140 offset1:206
	v_add_u32_e32 v35, 0x800, v43
	ds_write2_b32 v35, v10, v11 offset0:16 offset1:82
	ds_write2_b32 v35, v12, v13 offset0:148 offset1:214
	v_add_u32_e32 v35, 0xc00, v43
	v_readfirstlane_b32 s100, v237
	s_cmp_gt_u32 s100, 63
	s_cbranch_scc1 .Lmy_cv3_w
	s_mov_b64 s[44:45], exec
	s_mov_b64 exec, 1
	s_lshl_b32 s100, s40, 8
	s_add_i32 s100, s100, 0x5000
	v_mov_b32_e32 v90, s100
	v_mov_b32_e32 v91, 1
	global_atomic_add v91, v90, v91, s[36:37] sc0
	v_mov_b32_e32 v90, 0x21008
	s_waitcnt vmcnt(0)
	ds_write_b32 v90, v91
	s_waitcnt lgkmcnt(0)
	s_mov_b64 exec, s[44:45]
.Lmy_cv3_w:
	s_barrier
	v_mov_b32_e32 v90, 0x21008
	ds_read_b32 v90, v90
	s_waitcnt lgkmcnt(0)
	s_barrier
	v_readfirstlane_b32 s13, v90
	v_readfirstlane_b32 s100, v237
	s_lshr_b32 s100, s100, 6
	s_lshl_b32 s13, s13, 3
	s_add_i32 s13, s13, s100
	ds_write2_b32 v35, v14, v15 offset0:24 offset1:90
	ds_write2_b32 v35, v16, v17 offset0:156 offset1:222
	v_add_u32_e32 v35, 0x1000, v43
	ds_write2_b32 v35, v18, v19 offset0:32 offset1:98
	ds_write2_b32 v35, v20, v21 offset0:164 offset1:230
	v_add_u32_e32 v35, 0x1400, v43
	s_cmpk_gt_i32 s13, 0x11ff
	ds_write2_b32 v35, v22, v23 offset0:40 offset1:106
	ds_write2_b32 v35, v24, v25 offset0:172 offset1:238
	v_add_u32_e32 v35, 0x1800, v43
	s_cselect_b64 s[8:9], -1, 0
	ds_write2_b32 v35, v26, v27 offset0:48 offset1:114
	ds_write2_b32 v35, v28, v29 offset0:180 offset1:246
	v_add_u32_e32 v35, 0x1c00, v43
	s_and_b64 vcc, exec, s[8:9]
	ds_write2_b32 v35, v30, v31 offset0:56 offset1:122
	ds_write2_b32 v35, v32, v33 offset0:188 offset1:254
	s_cbranch_vccnz .LBB0_371
	s_cmpk_gt_i32 s13, 0xbff
	s_cselect_b64 s[4:5], -1, 0
	s_and_b64 s[10:11], s[4:5], exec
	s_cselect_b32 s19, 0x400, s85
	s_cselect_b32 s10, 0xfffff400, 0
	s_lshr_b32 s20, s19, 5
	s_abs_i32 s11, s20
	v_cvt_f32_u32_e32 v2, s11
	s_sub_i32 s23, 0, s11
	s_add_i32 s21, s13, s10
	v_rcp_iflag_f32_e32 v2, v2
	s_abs_i32 s22, s21
	s_xor_b32 s10, s21, s20
	s_ashr_i32 s10, s10, 31
	v_mul_f32_e32 v2, 0x4f7ffffe, v2
	v_cvt_u32_f32_e32 v2, v2
	v_mov_b32_e32 v8, 1.0
	v_readfirstlane_b32 s24, v2
	s_mul_i32 s23, s23, s24
	s_mul_hi_u32 s23, s24, s23
	s_add_i32 s24, s24, s23
	s_mul_hi_u32 s23, s22, s24
	s_mul_i32 s24, s23, s11
	s_sub_i32 s22, s22, s24
	s_add_i32 s25, s23, 1
	s_sub_i32 s24, s22, s11
	s_cmp_ge_u32 s22, s11
	s_cselect_b32 s23, s25, s23
	s_cselect_b32 s22, s24, s22
	s_add_i32 s24, s23, 1
	s_cmp_ge_u32 s22, s11
	s_cselect_b32 s11, s24, s23
	s_xor_b32 s11, s11, s10
	s_sub_i32 s22, s11, s10
	v_lshl_or_b32 v2, s22, 6, v38
	s_or_b64 s[10:11], s[4:5], s[92:93]
	v_ashrrev_i32_e32 v3, 31, v2
	s_and_b64 vcc, exec, s[10:11]
	v_lshl_add_u64 v[6:7], v[2:3], 2, s[6:7]
	v_mov_b32_e32 v3, 1.0
	s_cbranch_vccnz .LBB0_375
	global_load_dword v3, v[6:7], off

.LBB0_437:
	s_mov_b32 s12, s101
	v_lshlrev_b32_e32 v0, 2, v36
	v_lshl_or_b32 v2, s12, 8, v0
	s_mov_b32 s4, 0x20000
	v_cmp_gt_i32_e32 vcc, s4, v2
	s_and_saveexec_b64 s[4:5], vcc
	v_readlane_b32 s10, v255, 37
	v_readlane_b32 s11, v255, 38
	s_cbranch_execz .LBB0_440
	s_load_dwordx2 s[6:7], s[0:1], 0x48
	s_lshl_b64 s[8:9], s[40:41], 17
	s_and_b32 s8, s8, 0xfffc0000
	s_add_u32 s8, s8, 0x40000
	s_addc_u32 s9, s9, 0
	s_and_b32 s8, s8, 0xfff80000
	s_waitcnt lgkmcnt(0)
	s_add_u32 s6, s6, s8
	v_ashrrev_i32_e32 v3, 31, v2
	s_addc_u32 s7, s7, s9
	v_lshl_add_u64 v[4:5], v[2:3], 2, s[6:7]
	v_readlane_b32 s6, v254, 1
	v_readlane_b32 s7, v254, 2
	s_nop 1
	v_lshl_add_u64 v[6:7], v[2:3], 1, s[6:7]
	s_mov_b64 s[6:7], 0
